# baseline (speedup 1.0000x reference)
; DI float frcp(float x) { return __builtin_amdgcn_rcpf(x); }
; DI float bflo(unsigned w) { return __uint_as_float(w << 16); }
; DI float bfhi(unsigned w) { return __uint_as_float(w & 0xffff0000u); }
; DI u32x4 pack8(const f32x4 a, const f32x4 b) { u32x4 w; w.x = cvt_pk_bf16(a[0], a[1]); w.y = cvt_pk_bf16(a[2], a[3]); w.z = cvt_pk_bf16(b[0], b[1]); w.w = cvt_pk_bf16(b[2], b[3]); return w; }
;     DI void operator()(const pg8::f32x4 (&acc)[2][2][4][2], const pg8::Unit& u, int wr, int wc, int fr, int fq) const {
;     ...
;         for (int ai = 0; ai < 2; ++ai)
; #pragma unroll
;             for (int m = 0; m < 4; ++m) {
;                 const int r = u.pm * 256 + ai * 128 + wr * 64 + m * 16 + fr;
; #pragma unroll
;                 for (int bj = 0; bj < 2; ++bj) {
;                     const int c0 = u.pn * 256 + bj * 128 + wc * 32 + 8 * fq;
;                     const u32x4 zz = *(const u32x4*)(Z + (size_t)r * SW + c0);
;                     const f32x4 b0 = *(const f32x4*)(bias + c0), b1 = *(const f32x4*)(bias + c0 + 4);
;                     const f32x4 x0 = acc[ai][bj][m][0] + b0, x1 = acc[ai][bj][m][1] + b1;
;                     f32x4 o0, o1;
;                     o0[0] = bflo(zz.x) * frcp(1.f + __expf(-x0[0])); o0[1] = bfhi(zz.x) * frcp(1.f + __expf(-x0[1]));
;                     o0[2] = bflo(zz.y) * frcp(1.f + __expf(-x0[2])); o0[3] = bfhi(zz.y) * frcp(1.f + __expf(-x0[3]));
;                     o1[0] = bflo(zz.z) * frcp(1.f + __expf(-x1[0])); o1[1] = bfhi(zz.z) * frcp(1.f + __expf(-x1[1]));
;                     o1[2] = bflo(zz.w) * frcp(1.f + __expf(-x1[2])); o1[3] = bfhi(zz.w) * frcp(1.f + __expf(-x1[3]));
;                     *(u32x4*)(S + (size_t)r * SW + c0) = pack8(o0, o1);
.LBB0_530:
	v_lshl_add_u32 v140, s35, 8, v146
	v_ashrrev_i32_e32 v141, 31, v140
	v_lshl_add_u64 v[138:139], v[140:141], 2, s[40:41]
	global_load_dwordx4 v[166:169], v[138:139], off
	global_load_dwordx4 v[170:173], v[138:139], off offset:16
	global_load_dwordx4 v[174:177], v[138:139], off offset:512
	global_load_dwordx4 v[178:181], v[138:139], off offset:528
	v_lshl_add_u32 v142, s52, 8, v144
	v_ashrrev_i32_e32 v143, 31, v142
	v_lshlrev_b64 v[162:163], 11, v[142:143]
	v_lshlrev_b64 v[140:141], 1, v[140:141]
	v_lshl_add_u64 v[156:157], s[12:13], 0, v[162:163]
	v_lshl_add_u64 v[164:165], v[156:157], 0, v[140:141]
	global_load_dwordx4 v[182:185], v[164:165], off
	global_load_dwordx4 v[186:189], v[164:165], off offset:256
	v_add_co_u32_e32 v238, vcc, 0x8000, v164
	s_nop 1
	v_addc_co_u32_e32 v239, vcc, 0, v165, vcc
	global_load_dwordx4 v[190:193], v[238:239], off
	global_load_dwordx4 v[194:197], v[238:239], off offset:256
	v_add_co_u32_e32 v238, vcc, 0x10000, v164
	s_nop 1
	v_addc_co_u32_e32 v239, vcc, 0, v165, vcc
	global_load_dwordx4 v[198:201], v[238:239], off
	global_load_dwordx4 v[202:205], v[238:239], off offset:256
	v_add_co_u32_e32 v238, vcc, 0x18000, v164
	s_nop 1
	v_addc_co_u32_e32 v239, vcc, 0, v165, vcc
	global_load_dwordx4 v[206:209], v[238:239], off
	global_load_dwordx4 v[210:213], v[238:239], off offset:256
	v_add_co_u32_e32 v214, vcc, 0x40000, v164
	s_nop 1
	v_addc_co_u32_e32 v215, vcc, 0, v165, vcc
	v_add_co_u32_e32 v216, vcc, 0x48000, v164
	s_nop 1
	v_addc_co_u32_e32 v217, vcc, 0, v165, vcc
	v_add_co_u32_e32 v234, vcc, 0x50000, v164
	s_nop 1
	v_addc_co_u32_e32 v235, vcc, 0, v165, vcc
	v_add_co_u32_e32 v236, vcc, 0x58000, v164
	s_nop 1
	v_addc_co_u32_e32 v237, vcc, 0, v165, vcc
	s_andn2_b64 vcc, exec, s[36:37]
	s_mov_b64 s[14:15], -1
	s_waitcnt vmcnt(0)
	v_mov_b64_e32 v[148:149], v[166:167]
	v_mov_b64_e32 v[150:151], v[168:169]
	v_mov_b64_e32 v[152:153], v[170:171]
	v_mov_b64_e32 v[154:155], v[172:173]
	v_mov_b64_e32 v[156:157], v[182:183]
	v_mov_b64_e32 v[158:159], v[184:185]
	v_pk_add_f32 v[126:127], v[126:127], v[150:151]
	v_pk_add_f32 v[124:125], v[124:125], v[148:149]
	v_pk_add_f32 v[122:123], v[122:123], v[154:155]
	v_pk_add_f32 v[120:121], v[120:121], v[152:153]
	v_mul_f32_e32 v125, 0xbfb8aa3b, v125
	v_mul_f32_e32 v126, 0xbfb8aa3b, v126
	v_mul_f32_e32 v121, 0xbfb8aa3b, v121
	v_mul_f32_e32 v122, 0xbfb8aa3b, v122
	v_mul_f32_e32 v123, 0xbfb8aa3b, v123
	v_mul_f32_e32 v124, 0xbfb8aa3b, v124
	v_mul_f32_e32 v127, 0xbfb8aa3b, v127
	v_mul_f32_e32 v120, 0xbfb8aa3b, v120
	v_exp_f32_e32 v125, v125
	v_exp_f32_e32 v126, v126
	v_exp_f32_e32 v121, v121
	v_exp_f32_e32 v122, v122
	v_exp_f32_e32 v123, v123
	v_exp_f32_e32 v124, v124
	v_exp_f32_e32 v127, v127
	v_exp_f32_e32 v120, v120
	v_add_f32_e32 v125, 1.0, v125
	v_add_f32_e32 v126, 1.0, v126
	v_add_f32_e32 v121, 1.0, v121
	v_add_f32_e32 v122, 1.0, v122
	v_add_f32_e32 v123, 1.0, v123
	v_add_f32_e32 v124, 1.0, v124
	v_add_f32_e32 v127, 1.0, v127
	v_add_f32_e32 v120, 1.0, v120
	v_rcp_f32_e32 v125, v125
	v_rcp_f32_e32 v126, v126
	v_rcp_f32_e32 v121, v121
	v_rcp_f32_e32 v122, v122
	v_rcp_f32_e32 v123, v123
	v_rcp_f32_e32 v124, v124
	v_rcp_f32_e32 v127, v127
	v_rcp_f32_e32 v120, v120
	v_and_b32_e32 v148, 0xffff0000, v156
	v_lshlrev_b32_e32 v149, 16, v157
	v_and_b32_e32 v152, 0xffff0000, v158
	v_lshlrev_b32_e32 v153, 16, v159
	v_and_b32_e32 v154, 0xffff0000, v159
	v_lshlrev_b32_e32 v143, 16, v156
	v_and_b32_e32 v150, 0xffff0000, v157
	v_lshlrev_b32_e32 v151, 16, v158
	v_mul_f32_e32 v125, v125, v148
	v_mul_f32_e32 v126, v126, v149
	v_mul_f32_e32 v148, v121, v152
	v_mul_f32_e32 v149, v122, v153
	v_mul_f32_e32 v123, v123, v154
	v_mul_f32_e32 v124, v124, v143
	v_mul_f32_e32 v127, v127, v150
	v_mul_f32_e32 v143, v120, v151
	v_cvt_pk_bf16_f32 v120, v124, v125
	v_cvt_pk_bf16_f32 v121, v126, v127
	v_cvt_pk_bf16_f32 v122, v143, v148
	v_cvt_pk_bf16_f32 v123, v149, v123
	v_lshl_add_u64 v[148:149], s[10:11], 0, v[162:163]
	v_lshl_add_u64 v[152:153], v[148:149], 0, v[140:141]
	global_store_dwordx4 v[152:153], v[120:123], off
	v_mov_b64_e32 v[124:125], v[186:187]
	v_mov_b64_e32 v[126:127], v[188:189]
	s_nop 0
	v_mov_b64_e32 v[120:121], v[174:175]
	v_mov_b64_e32 v[122:123], v[176:177]
	v_mov_b64_e32 v[148:149], v[178:179]
	v_mov_b64_e32 v[150:151], v[180:181]
	v_or_b32_e32 v154, 16, v142
	v_ashrrev_i32_e32 v155, 31, v154
	v_lshlrev_b64 v[154:155], 11, v[154:155]
	v_lshl_add_u64 v[156:157], s[12:13], 0, v[154:155]
	v_lshl_add_u64 v[156:157], v[156:157], 0, v[140:141]
	v_lshlrev_b32_e32 v162, 16, v127
	v_pk_add_f32 v[114:115], v[114:115], v[150:151]
	v_pk_add_f32 v[118:119], v[118:119], v[122:123]
	v_pk_add_f32 v[116:117], v[116:117], v[120:121]
	v_pk_add_f32 v[112:113], v[112:113], v[148:149]
	v_mul_f32_e32 v115, 0xbfb8aa3b, v115
	v_mul_f32_e32 v116, 0xbfb8aa3b, v116
	v_mul_f32_e32 v117, 0xbfb8aa3b, v117
	v_mul_f32_e32 v118, 0xbfb8aa3b, v118
	v_mul_f32_e32 v119, 0xbfb8aa3b, v119
	v_mul_f32_e32 v112, 0xbfb8aa3b, v112
	v_mul_f32_e32 v113, 0xbfb8aa3b, v113
	v_mul_f32_e32 v114, 0xbfb8aa3b, v114
	v_exp_f32_e32 v115, v115
	v_exp_f32_e32 v116, v116
	v_exp_f32_e32 v117, v117
	v_exp_f32_e32 v118, v118
	v_exp_f32_e32 v119, v119
	v_exp_f32_e32 v112, v112
	v_exp_f32_e32 v113, v113
	v_exp_f32_e32 v114, v114
	v_add_f32_e32 v115, 1.0, v115
	v_add_f32_e32 v116, 1.0, v116
	v_add_f32_e32 v117, 1.0, v117
	v_add_f32_e32 v118, 1.0, v118
	v_add_f32_e32 v119, 1.0, v119
	v_add_f32_e32 v112, 1.0, v112
	v_add_f32_e32 v113, 1.0, v113
	v_add_f32_e32 v114, 1.0, v114
	v_rcp_f32_e32 v115, v115
	v_rcp_f32_e32 v116, v116
	v_rcp_f32_e32 v117, v117
	v_rcp_f32_e32 v118, v118
	v_rcp_f32_e32 v119, v119
	v_rcp_f32_e32 v112, v112
	v_rcp_f32_e32 v113, v113
; DI float frcp(float x) { return __builtin_amdgcn_rcpf(x); }
; DI float bflo(unsigned w) { return __uint_as_float(w << 16); }
; DI float bfhi(unsigned w) { return __uint_as_float(w & 0xffff0000u); }
; DI u32x4 pack8(const f32x4 a, const f32x4 b) { u32x4 w; w.x = cvt_pk_bf16(a[0], a[1]); w.y = cvt_pk_bf16(a[2], a[3]); w.z = cvt_pk_bf16(b[0], b[1]); w.w = cvt_pk_bf16(b[2], b[3]); return w; }
;     DI void operator()(const pg8::f32x4 (&acc)[2][2][4][2], const pg8::Unit& u, int wr, int wc, int fr, int fq) const {
;     ...
;         for (int ai = 0; ai < 2; ++ai)
; #pragma unroll
;             for (int m = 0; m < 4; ++m) {
;                 const int r = u.pm * 256 + ai * 128 + wr * 64 + m * 16 + fr;
; #pragma unroll
;                 for (int bj = 0; bj < 2; ++bj) {
;                     const int c0 = u.pn * 256 + bj * 128 + wc * 32 + 8 * fq;
;                     const u32x4 zz = *(const u32x4*)(Z + (size_t)r * SW + c0);
;                     const f32x4 b0 = *(const f32x4*)(bias + c0), b1 = *(const f32x4*)(bias + c0 + 4);
;                     const f32x4 x0 = acc[ai][bj][m][0] + b0, x1 = acc[ai][bj][m][1] + b1;
;                     f32x4 o0, o1;
;                     o0[0] = bflo(zz.x) * frcp(1.f + __expf(-x0[0])); o0[1] = bfhi(zz.x) * frcp(1.f + __expf(-x0[1]));
;                     o0[2] = bflo(zz.y) * frcp(1.f + __expf(-x0[2])); o0[3] = bfhi(zz.y) * frcp(1.f + __expf(-x0[3]));
;                     o1[0] = bflo(zz.z) * frcp(1.f + __expf(-x1[0])); o1[1] = bfhi(zz.z) * frcp(1.f + __expf(-x1[1]));
;                     o1[2] = bflo(zz.w) * frcp(1.f + __expf(-x1[2])); o1[3] = bfhi(zz.w) * frcp(1.f + __expf(-x1[3]));
;                     *(u32x4*)(S + (size_t)r * SW + c0) = pack8(o0, o1);
	v_rcp_f32_e32 v114, v114
	v_and_b32_e32 v127, 0xffff0000, v127
	v_lshlrev_b32_e32 v143, 16, v124
	v_and_b32_e32 v124, 0xffff0000, v124
	v_lshlrev_b32_e32 v158, 16, v125
	v_and_b32_e32 v125, 0xffff0000, v125
	v_lshlrev_b32_e32 v159, 16, v126
	v_and_b32_e32 v126, 0xffff0000, v126
	v_mul_f32_e32 v115, v115, v127
	v_mul_f32_e32 v116, v116, v143
	v_mul_f32_e32 v117, v117, v124
	v_mul_f32_e32 v118, v118, v158
	v_mul_f32_e32 v119, v119, v125
	v_mul_f32_e32 v120, v112, v159
	v_mul_f32_e32 v121, v113, v126
	v_mul_f32_e32 v122, v114, v162
	v_cvt_pk_bf16_f32 v112, v116, v117
	v_cvt_pk_bf16_f32 v113, v118, v119
	v_cvt_pk_bf16_f32 v114, v120, v121
	v_cvt_pk_bf16_f32 v115, v122, v115
	global_store_dwordx4 v[152:153], v[112:115], off offset:256
	v_mov_b64_e32 v[116:117], v[190:191]
	v_mov_b64_e32 v[118:119], v[192:193]
	s_nop 0
	v_mov_b64_e32 v[112:113], v[166:167]
	v_mov_b64_e32 v[114:115], v[168:169]
	v_mov_b64_e32 v[120:121], v[170:171]
	v_mov_b64_e32 v[122:123], v[172:173]
	v_pk_add_f32 v[110:111], v[110:111], v[114:115]
	v_pk_add_f32 v[104:105], v[104:105], v[120:121]
	v_pk_add_f32 v[108:109], v[108:109], v[112:113]
	v_pk_add_f32 v[106:107], v[106:107], v[122:123]
	v_mul_f32_e32 v104, 0xbfb8aa3b, v104
	v_mul_f32_e32 v105, 0xbfb8aa3b, v105
	v_mul_f32_e32 v108, 0xbfb8aa3b, v108
	v_mul_f32_e32 v109, 0xbfb8aa3b, v109
	v_mul_f32_e32 v110, 0xbfb8aa3b, v110
	v_mul_f32_e32 v111, 0xbfb8aa3b, v111
	v_mul_f32_e32 v106, 0xbfb8aa3b, v106
	v_exp_f32_e32 v104, v104
	v_exp_f32_e32 v105, v105
	v_mul_f32_e32 v107, 0xbfb8aa3b, v107
	v_exp_f32_e32 v108, v108
	v_exp_f32_e32 v109, v109
	v_exp_f32_e32 v110, v110
	v_exp_f32_e32 v111, v111
	v_exp_f32_e32 v106, v106
	v_exp_f32_e32 v107, v107
	v_add_f32_e32 v104, 1.0, v104
	v_add_f32_e32 v105, 1.0, v105
	v_add_f32_e32 v108, 1.0, v108
	v_add_f32_e32 v109, 1.0, v109
	v_add_f32_e32 v110, 1.0, v110
	v_add_f32_e32 v111, 1.0, v111
	v_add_f32_e32 v106, 1.0, v106
	v_rcp_f32_e32 v104, v104
	v_rcp_f32_e32 v105, v105
	v_add_f32_e32 v107, 1.0, v107
	v_rcp_f32_e32 v108, v108
	v_rcp_f32_e32 v109, v109
	v_rcp_f32_e32 v110, v110
	v_rcp_f32_e32 v111, v111
	v_rcp_f32_e32 v106, v106
	v_rcp_f32_e32 v107, v107
	v_lshlrev_b32_e32 v126, 16, v118
	v_and_b32_e32 v118, 0xffff0000, v118
	v_lshlrev_b32_e32 v124, 16, v116
	v_and_b32_e32 v116, 0xffff0000, v116
	v_lshlrev_b32_e32 v125, 16, v117
	v_and_b32_e32 v117, 0xffff0000, v117
	v_lshlrev_b32_e32 v127, 16, v119
	v_mul_f32_e32 v112, v104, v126
	v_mul_f32_e32 v113, v105, v118
	v_and_b32_e32 v119, 0xffff0000, v119
	v_mul_f32_e32 v108, v108, v124
	v_mul_f32_e32 v109, v109, v116
	v_mul_f32_e32 v110, v110, v125
	v_mul_f32_e32 v111, v111, v117
	v_mul_f32_e32 v114, v106, v127
	v_cvt_pk_bf16_f32 v104, v108, v109
	v_cvt_pk_bf16_f32 v105, v110, v111
	v_cvt_pk_bf16_f32 v106, v112, v113
	v_lshl_add_u64 v[112:113], s[10:11], 0, v[154:155]
	v_mul_f32_e32 v107, v107, v119
	v_lshl_add_u64 v[116:117], v[112:113], 0, v[140:141]
	v_cvt_pk_bf16_f32 v107, v114, v107
	global_store_dwordx4 v[116:117], v[104:107], off
	v_mov_b64_e32 v[108:109], v[194:195]
	v_mov_b64_e32 v[110:111], v[196:197]
	s_nop 0
	v_mov_b64_e32 v[104:105], v[174:175]
	v_mov_b64_e32 v[106:107], v[176:177]
	v_mov_b64_e32 v[112:113], v[178:179]
	v_mov_b64_e32 v[114:115], v[180:181]
	v_or_b32_e32 v118, 32, v142
	v_ashrrev_i32_e32 v119, 31, v118
	v_lshlrev_b64 v[118:119], 11, v[118:119]
	v_lshl_add_u64 v[120:121], s[12:13], 0, v[118:119]
	v_lshl_add_u64 v[120:121], v[120:121], 0, v[140:141]
	v_pk_add_f32 v[102:103], v[102:103], v[106:107]
	v_pk_add_f32 v[98:99], v[98:99], v[114:115]
	v_pk_add_f32 v[100:101], v[100:101], v[104:105]
	v_pk_add_f32 v[96:97], v[96:97], v[112:113]
	v_mul_f32_e32 v99, 0xbfb8aa3b, v99
	v_mul_f32_e32 v100, 0xbfb8aa3b, v100
	v_mul_f32_e32 v101, 0xbfb8aa3b, v101
	v_mul_f32_e32 v102, 0xbfb8aa3b, v102
	v_mul_f32_e32 v103, 0xbfb8aa3b, v103
	v_mul_f32_e32 v96, 0xbfb8aa3b, v96
	v_mul_f32_e32 v97, 0xbfb8aa3b, v97
	v_mul_f32_e32 v98, 0xbfb8aa3b, v98
	v_exp_f32_e32 v99, v99
	v_exp_f32_e32 v100, v100
	v_exp_f32_e32 v101, v101
	v_exp_f32_e32 v102, v102
	v_exp_f32_e32 v103, v103
	v_exp_f32_e32 v96, v96
	v_exp_f32_e32 v97, v97
	v_exp_f32_e32 v98, v98
	v_add_f32_e32 v99, 1.0, v99
	v_add_f32_e32 v100, 1.0, v100
	v_add_f32_e32 v101, 1.0, v101
	v_add_f32_e32 v102, 1.0, v102
	v_add_f32_e32 v103, 1.0, v103
	v_add_f32_e32 v96, 1.0, v96
	v_add_f32_e32 v97, 1.0, v97
	v_add_f32_e32 v98, 1.0, v98
	v_rcp_f32_e32 v99, v99
	v_rcp_f32_e32 v100, v100
	v_rcp_f32_e32 v101, v101
	v_rcp_f32_e32 v102, v102
	v_rcp_f32_e32 v103, v103
	v_rcp_f32_e32 v96, v96
	v_rcp_f32_e32 v97, v97
	v_rcp_f32_e32 v98, v98
	v_lshlrev_b32_e32 v125, 16, v111
	v_and_b32_e32 v111, 0xffff0000, v111
	v_lshlrev_b32_e32 v122, 16, v108
	v_and_b32_e32 v108, 0xffff0000, v108
	v_lshlrev_b32_e32 v123, 16, v109
	v_and_b32_e32 v109, 0xffff0000, v109
	v_lshlrev_b32_e32 v124, 16, v110
	v_and_b32_e32 v110, 0xffff0000, v110
	v_mul_f32_e32 v99, v99, v111
	v_mul_f32_e32 v100, v100, v122
	v_mul_f32_e32 v101, v101, v108
	v_mul_f32_e32 v102, v102, v123
	v_mul_f32_e32 v103, v103, v109
	v_mul_f32_e32 v104, v96, v124
	v_mul_f32_e32 v105, v97, v110
	v_mul_f32_e32 v106, v98, v125
	v_cvt_pk_bf16_f32 v96, v100, v101
	v_cvt_pk_bf16_f32 v97, v102, v103
	v_cvt_pk_bf16_f32 v98, v104, v105
	v_cvt_pk_bf16_f32 v99, v106, v99
	global_store_dwordx4 v[116:117], v[96:99], off offset:256
	v_mov_b64_e32 v[100:101], v[198:199]
	v_mov_b64_e32 v[102:103], v[200:201]
	s_nop 0
	v_mov_b64_e32 v[96:97], v[166:167]
	v_mov_b64_e32 v[98:99], v[168:169]
	v_mov_b64_e32 v[104:105], v[170:171]
	v_mov_b64_e32 v[106:107], v[172:173]
	v_pk_add_f32 v[94:95], v[94:95], v[98:99]
	v_pk_add_f32 v[88:89], v[88:89], v[104:105]
	v_pk_add_f32 v[92:93], v[92:93], v[96:97]
; DI float frcp(float x) { return __builtin_amdgcn_rcpf(x); }
; DI float bflo(unsigned w) { return __uint_as_float(w << 16); }
; DI float bfhi(unsigned w) { return __uint_as_float(w & 0xffff0000u); }
; DI u32x4 pack8(const f32x4 a, const f32x4 b) { u32x4 w; w.x = cvt_pk_bf16(a[0], a[1]); w.y = cvt_pk_bf16(a[2], a[3]); w.z = cvt_pk_bf16(b[0], b[1]); w.w = cvt_pk_bf16(b[2], b[3]); return w; }
;     DI void operator()(const pg8::f32x4 (&acc)[2][2][4][2], const pg8::Unit& u, int wr, int wc, int fr, int fq) const {
;     ...
;         for (int ai = 0; ai < 2; ++ai)
; #pragma unroll
;             for (int m = 0; m < 4; ++m) {
;                 const int r = u.pm * 256 + ai * 128 + wr * 64 + m * 16 + fr;
; #pragma unroll
;                 for (int bj = 0; bj < 2; ++bj) {
;                     const int c0 = u.pn * 256 + bj * 128 + wc * 32 + 8 * fq;
;                     const u32x4 zz = *(const u32x4*)(Z + (size_t)r * SW + c0);
;                     const f32x4 b0 = *(const f32x4*)(bias + c0), b1 = *(const f32x4*)(bias + c0 + 4);
;                     const f32x4 x0 = acc[ai][bj][m][0] + b0, x1 = acc[ai][bj][m][1] + b1;
;                     f32x4 o0, o1;
;                     o0[0] = bflo(zz.x) * frcp(1.f + __expf(-x0[0])); o0[1] = bfhi(zz.x) * frcp(1.f + __expf(-x0[1]));
;                     o0[2] = bflo(zz.y) * frcp(1.f + __expf(-x0[2])); o0[3] = bfhi(zz.y) * frcp(1.f + __expf(-x0[3]));
;                     o1[0] = bflo(zz.z) * frcp(1.f + __expf(-x1[0])); o1[1] = bfhi(zz.z) * frcp(1.f + __expf(-x1[1]));
;                     o1[2] = bflo(zz.w) * frcp(1.f + __expf(-x1[2])); o1[3] = bfhi(zz.w) * frcp(1.f + __expf(-x1[3]));
;                     *(u32x4*)(S + (size_t)r * SW + c0) = pack8(o0, o1);
	v_pk_add_f32 v[90:91], v[90:91], v[106:107]
	v_mul_f32_e32 v88, 0xbfb8aa3b, v88
	v_mul_f32_e32 v89, 0xbfb8aa3b, v89
	v_mul_f32_e32 v92, 0xbfb8aa3b, v92
	v_mul_f32_e32 v93, 0xbfb8aa3b, v93
	v_mul_f32_e32 v94, 0xbfb8aa3b, v94
	v_mul_f32_e32 v95, 0xbfb8aa3b, v95
	v_mul_f32_e32 v90, 0xbfb8aa3b, v90
	v_exp_f32_e32 v88, v88
	v_exp_f32_e32 v89, v89
	v_mul_f32_e32 v91, 0xbfb8aa3b, v91
	v_exp_f32_e32 v92, v92
	v_exp_f32_e32 v93, v93
	v_exp_f32_e32 v94, v94
	v_exp_f32_e32 v95, v95
	v_exp_f32_e32 v90, v90
	v_exp_f32_e32 v91, v91
	v_add_f32_e32 v88, 1.0, v88
	v_add_f32_e32 v89, 1.0, v89
	v_add_f32_e32 v92, 1.0, v92
	v_add_f32_e32 v93, 1.0, v93
	v_add_f32_e32 v94, 1.0, v94
	v_add_f32_e32 v95, 1.0, v95
	v_add_f32_e32 v90, 1.0, v90
	v_rcp_f32_e32 v88, v88
	v_rcp_f32_e32 v89, v89
	v_add_f32_e32 v91, 1.0, v91
	v_rcp_f32_e32 v92, v92
	v_rcp_f32_e32 v93, v93
	v_rcp_f32_e32 v94, v94
	v_rcp_f32_e32 v95, v95
	v_rcp_f32_e32 v90, v90
	v_rcp_f32_e32 v91, v91
	v_lshlrev_b32_e32 v110, 16, v102
	v_and_b32_e32 v102, 0xffff0000, v102
	v_lshlrev_b32_e32 v108, 16, v100
	v_and_b32_e32 v100, 0xffff0000, v100
	v_lshlrev_b32_e32 v109, 16, v101
	v_and_b32_e32 v101, 0xffff0000, v101
	v_lshlrev_b32_e32 v111, 16, v103
	v_mul_f32_e32 v96, v88, v110
	v_mul_f32_e32 v97, v89, v102
	v_and_b32_e32 v103, 0xffff0000, v103
	v_mul_f32_e32 v92, v92, v108
	v_mul_f32_e32 v93, v93, v100
	v_mul_f32_e32 v94, v94, v109
	v_mul_f32_e32 v95, v95, v101
	v_mul_f32_e32 v98, v90, v111
	v_cvt_pk_bf16_f32 v88, v92, v93
	v_cvt_pk_bf16_f32 v89, v94, v95
	v_cvt_pk_bf16_f32 v90, v96, v97
	v_lshl_add_u64 v[96:97], s[10:11], 0, v[118:119]
	v_mul_f32_e32 v91, v91, v103
	v_lshl_add_u64 v[100:101], v[96:97], 0, v[140:141]
	v_cvt_pk_bf16_f32 v91, v98, v91
	global_store_dwordx4 v[100:101], v[88:91], off
	v_mov_b64_e32 v[92:93], v[202:203]
	v_mov_b64_e32 v[94:95], v[204:205]
	s_nop 0
	v_mov_b64_e32 v[88:89], v[174:175]
	v_mov_b64_e32 v[90:91], v[176:177]
	v_mov_b64_e32 v[96:97], v[178:179]
	v_mov_b64_e32 v[98:99], v[180:181]
	v_or_b32_e32 v102, 48, v142
	v_ashrrev_i32_e32 v103, 31, v102
	v_lshlrev_b64 v[102:103], 11, v[102:103]
	v_lshl_add_u64 v[104:105], s[12:13], 0, v[102:103]
	v_lshl_add_u64 v[104:105], v[104:105], 0, v[140:141]
	v_pk_add_f32 v[86:87], v[86:87], v[90:91]
	v_pk_add_f32 v[82:83], v[82:83], v[98:99]
	v_pk_add_f32 v[84:85], v[84:85], v[88:89]
	v_pk_add_f32 v[80:81], v[80:81], v[96:97]
	v_mul_f32_e32 v83, 0xbfb8aa3b, v83
	v_mul_f32_e32 v84, 0xbfb8aa3b, v84
	v_mul_f32_e32 v85, 0xbfb8aa3b, v85
	v_mul_f32_e32 v86, 0xbfb8aa3b, v86
	v_mul_f32_e32 v87, 0xbfb8aa3b, v87
	v_mul_f32_e32 v80, 0xbfb8aa3b, v80
	v_mul_f32_e32 v81, 0xbfb8aa3b, v81
	v_mul_f32_e32 v82, 0xbfb8aa3b, v82
	v_exp_f32_e32 v83, v83
	v_exp_f32_e32 v84, v84
	v_exp_f32_e32 v85, v85
	v_exp_f32_e32 v86, v86
	v_exp_f32_e32 v87, v87
	v_exp_f32_e32 v80, v80
	v_exp_f32_e32 v81, v81
	v_exp_f32_e32 v82, v82
	v_add_f32_e32 v83, 1.0, v83
	v_add_f32_e32 v84, 1.0, v84
	v_add_f32_e32 v85, 1.0, v85
	v_add_f32_e32 v86, 1.0, v86
	v_add_f32_e32 v87, 1.0, v87
	v_add_f32_e32 v80, 1.0, v80
	v_add_f32_e32 v81, 1.0, v81
	v_add_f32_e32 v82, 1.0, v82
	v_rcp_f32_e32 v83, v83
	v_rcp_f32_e32 v84, v84
	v_rcp_f32_e32 v85, v85
	v_rcp_f32_e32 v86, v86
	v_rcp_f32_e32 v87, v87
	v_rcp_f32_e32 v80, v80
	v_rcp_f32_e32 v81, v81
	v_rcp_f32_e32 v82, v82
	v_lshlrev_b32_e32 v109, 16, v95
	v_and_b32_e32 v95, 0xffff0000, v95
	v_lshlrev_b32_e32 v106, 16, v92
	v_and_b32_e32 v92, 0xffff0000, v92
	v_lshlrev_b32_e32 v107, 16, v93
	v_and_b32_e32 v93, 0xffff0000, v93
	v_lshlrev_b32_e32 v108, 16, v94
	v_and_b32_e32 v94, 0xffff0000, v94
	v_mul_f32_e32 v83, v83, v95
	v_mul_f32_e32 v84, v84, v106
	v_mul_f32_e32 v85, v85, v92
	v_mul_f32_e32 v86, v86, v107
	v_mul_f32_e32 v87, v87, v93
	v_mul_f32_e32 v88, v80, v108
	v_mul_f32_e32 v89, v81, v94
	v_mul_f32_e32 v90, v82, v109
	v_cvt_pk_bf16_f32 v80, v84, v85
	v_cvt_pk_bf16_f32 v81, v86, v87
	v_cvt_pk_bf16_f32 v82, v88, v89
	v_cvt_pk_bf16_f32 v83, v90, v83
	global_store_dwordx4 v[100:101], v[80:83], off offset:256
	v_mov_b64_e32 v[84:85], v[206:207]
	v_mov_b64_e32 v[86:87], v[208:209]
	s_nop 0
	v_mov_b64_e32 v[80:81], v[166:167]
	v_mov_b64_e32 v[82:83], v[168:169]
	v_mov_b64_e32 v[88:89], v[170:171]
	v_mov_b64_e32 v[90:91], v[172:173]
	v_pk_add_f32 v[78:79], v[78:79], v[82:83]
	v_pk_add_f32 v[72:73], v[72:73], v[88:89]
	v_pk_add_f32 v[76:77], v[76:77], v[80:81]
	v_pk_add_f32 v[74:75], v[74:75], v[90:91]
	v_mul_f32_e32 v72, 0xbfb8aa3b, v72
	v_mul_f32_e32 v73, 0xbfb8aa3b, v73
	v_mul_f32_e32 v76, 0xbfb8aa3b, v76
	v_mul_f32_e32 v77, 0xbfb8aa3b, v77
	v_mul_f32_e32 v78, 0xbfb8aa3b, v78
	v_mul_f32_e32 v79, 0xbfb8aa3b, v79
	v_mul_f32_e32 v74, 0xbfb8aa3b, v74
	v_exp_f32_e32 v72, v72
	v_exp_f32_e32 v73, v73
	v_mul_f32_e32 v75, 0xbfb8aa3b, v75
	v_exp_f32_e32 v76, v76
	v_exp_f32_e32 v77, v77
	v_exp_f32_e32 v78, v78
	v_exp_f32_e32 v79, v79
	v_exp_f32_e32 v74, v74
	v_exp_f32_e32 v75, v75
	v_add_f32_e32 v72, 1.0, v72
	v_add_f32_e32 v73, 1.0, v73
	v_add_f32_e32 v76, 1.0, v76
	v_add_f32_e32 v77, 1.0, v77
	v_add_f32_e32 v78, 1.0, v78
	v_add_f32_e32 v79, 1.0, v79
	v_add_f32_e32 v74, 1.0, v74
	v_rcp_f32_e32 v72, v72
	v_rcp_f32_e32 v73, v73
	v_add_f32_e32 v75, 1.0, v75
	v_rcp_f32_e32 v76, v76
	v_rcp_f32_e32 v77, v77
	v_rcp_f32_e32 v78, v78
	v_rcp_f32_e32 v79, v79
	v_rcp_f32_e32 v74, v74
	v_rcp_f32_e32 v75, v75
	v_lshlrev_b32_e32 v94, 16, v86
	v_and_b32_e32 v86, 0xffff0000, v86
	v_lshlrev_b32_e32 v92, 16, v84
	v_and_b32_e32 v84, 0xffff0000, v84
	v_lshlrev_b32_e32 v93, 16, v85
	v_and_b32_e32 v85, 0xffff0000, v85
	v_lshlrev_b32_e32 v95, 16, v87
	v_mul_f32_e32 v80, v72, v94
	v_mul_f32_e32 v81, v73, v86
	v_and_b32_e32 v87, 0xffff0000, v87
	v_mul_f32_e32 v76, v76, v92
; DI float frcp(float x) { return __builtin_amdgcn_rcpf(x); }
; DI float bflo(unsigned w) { return __uint_as_float(w << 16); }
; DI float bfhi(unsigned w) { return __uint_as_float(w & 0xffff0000u); }
; DI u32x4 pack8(const f32x4 a, const f32x4 b) { u32x4 w; w.x = cvt_pk_bf16(a[0], a[1]); w.y = cvt_pk_bf16(a[2], a[3]); w.z = cvt_pk_bf16(b[0], b[1]); w.w = cvt_pk_bf16(b[2], b[3]); return w; }
;     DI void operator()(const pg8::f32x4 (&acc)[2][2][4][2], const pg8::Unit& u, int wr, int wc, int fr, int fq) const {
;     ...
;         for (int ai = 0; ai < 2; ++ai)
; #pragma unroll
;             for (int m = 0; m < 4; ++m) {
;                 const int r = u.pm * 256 + ai * 128 + wr * 64 + m * 16 + fr;
; #pragma unroll
;                 for (int bj = 0; bj < 2; ++bj) {
;                     const int c0 = u.pn * 256 + bj * 128 + wc * 32 + 8 * fq;
;                     const u32x4 zz = *(const u32x4*)(Z + (size_t)r * SW + c0);
;                     const f32x4 b0 = *(const f32x4*)(bias + c0), b1 = *(const f32x4*)(bias + c0 + 4);
;                     const f32x4 x0 = acc[ai][bj][m][0] + b0, x1 = acc[ai][bj][m][1] + b1;
;                     f32x4 o0, o1;
;                     o0[0] = bflo(zz.x) * frcp(1.f + __expf(-x0[0])); o0[1] = bfhi(zz.x) * frcp(1.f + __expf(-x0[1]));
;                     o0[2] = bflo(zz.y) * frcp(1.f + __expf(-x0[2])); o0[3] = bfhi(zz.y) * frcp(1.f + __expf(-x0[3]));
;                     o1[0] = bflo(zz.z) * frcp(1.f + __expf(-x1[0])); o1[1] = bfhi(zz.z) * frcp(1.f + __expf(-x1[1]));
;                     o1[2] = bflo(zz.w) * frcp(1.f + __expf(-x1[2])); o1[3] = bfhi(zz.w) * frcp(1.f + __expf(-x1[3]));
;                     *(u32x4*)(S + (size_t)r * SW + c0) = pack8(o0, o1);
	v_mul_f32_e32 v77, v77, v84
	v_mul_f32_e32 v78, v78, v93
	v_mul_f32_e32 v79, v79, v85
	v_mul_f32_e32 v82, v74, v95
	v_cvt_pk_bf16_f32 v72, v76, v77
	v_cvt_pk_bf16_f32 v73, v78, v79
	v_cvt_pk_bf16_f32 v74, v80, v81
	v_lshl_add_u64 v[80:81], s[10:11], 0, v[102:103]
	v_mul_f32_e32 v75, v75, v87
	v_lshl_add_u64 v[84:85], v[80:81], 0, v[140:141]
	v_cvt_pk_bf16_f32 v75, v82, v75
	global_store_dwordx4 v[84:85], v[72:75], off
	v_mov_b64_e32 v[76:77], v[210:211]
	v_mov_b64_e32 v[78:79], v[212:213]
	s_nop 0
	v_mov_b64_e32 v[72:73], v[174:175]
	v_mov_b64_e32 v[74:75], v[176:177]
	v_mov_b64_e32 v[80:81], v[178:179]
	v_mov_b64_e32 v[82:83], v[180:181]
	v_add_u32_e32 v86, 0x80, v142
	v_ashrrev_i32_e32 v87, 31, v86
	v_lshlrev_b64 v[86:87], 11, v[86:87]
	v_lshl_add_u64 v[88:89], s[12:13], 0, v[86:87]
	v_lshl_add_u64 v[88:89], v[88:89], 0, v[140:141]
	v_pk_add_f32 v[70:71], v[70:71], v[74:75]
	v_pk_add_f32 v[66:67], v[66:67], v[82:83]
	v_pk_add_f32 v[68:69], v[68:69], v[72:73]
	v_pk_add_f32 v[64:65], v[64:65], v[80:81]
	v_mul_f32_e32 v67, 0xbfb8aa3b, v67
	v_mul_f32_e32 v68, 0xbfb8aa3b, v68
	v_mul_f32_e32 v69, 0xbfb8aa3b, v69
	v_mul_f32_e32 v70, 0xbfb8aa3b, v70
	v_mul_f32_e32 v71, 0xbfb8aa3b, v71
	v_mul_f32_e32 v64, 0xbfb8aa3b, v64
	v_mul_f32_e32 v65, 0xbfb8aa3b, v65
	v_mul_f32_e32 v66, 0xbfb8aa3b, v66
	v_exp_f32_e32 v67, v67
	v_exp_f32_e32 v68, v68
	v_exp_f32_e32 v69, v69
	v_exp_f32_e32 v70, v70
	v_exp_f32_e32 v71, v71
	v_exp_f32_e32 v64, v64
	v_exp_f32_e32 v65, v65
	v_exp_f32_e32 v66, v66
	v_add_f32_e32 v67, 1.0, v67
	v_add_f32_e32 v68, 1.0, v68
	v_add_f32_e32 v69, 1.0, v69
	v_add_f32_e32 v70, 1.0, v70
	v_add_f32_e32 v71, 1.0, v71
	v_add_f32_e32 v64, 1.0, v64
	v_add_f32_e32 v65, 1.0, v65
	v_add_f32_e32 v66, 1.0, v66
	v_rcp_f32_e32 v67, v67
	v_rcp_f32_e32 v68, v68
	v_rcp_f32_e32 v69, v69
	v_rcp_f32_e32 v70, v70
	v_rcp_f32_e32 v71, v71
	v_rcp_f32_e32 v64, v64
	v_rcp_f32_e32 v65, v65
	v_rcp_f32_e32 v66, v66
	v_lshlrev_b32_e32 v93, 16, v79
	v_and_b32_e32 v79, 0xffff0000, v79
	v_lshlrev_b32_e32 v90, 16, v76
	v_and_b32_e32 v76, 0xffff0000, v76
	v_lshlrev_b32_e32 v91, 16, v77
	v_and_b32_e32 v77, 0xffff0000, v77
	v_lshlrev_b32_e32 v92, 16, v78
	v_and_b32_e32 v78, 0xffff0000, v78
	v_mul_f32_e32 v67, v67, v79
	v_mul_f32_e32 v68, v68, v90
	v_mul_f32_e32 v69, v69, v76
	v_mul_f32_e32 v70, v70, v91
	v_mul_f32_e32 v71, v71, v77
	v_mul_f32_e32 v72, v64, v92
	v_mul_f32_e32 v73, v65, v78
	v_mul_f32_e32 v74, v66, v93
	v_cvt_pk_bf16_f32 v64, v68, v69
	v_cvt_pk_bf16_f32 v65, v70, v71
	v_cvt_pk_bf16_f32 v66, v72, v73
	v_cvt_pk_bf16_f32 v67, v74, v67
	global_store_dwordx4 v[84:85], v[64:67], off offset:256
	global_load_dwordx4 v[182:185], v[214:215], off
	global_load_dwordx4 v[186:189], v[214:215], off offset:256
	global_load_dwordx4 v[190:193], v[216:217], off
	global_load_dwordx4 v[194:197], v[216:217], off offset:256
	global_load_dwordx4 v[198:201], v[234:235], off
	global_load_dwordx4 v[202:205], v[234:235], off offset:256
	global_load_dwordx4 v[206:209], v[236:237], off
	global_load_dwordx4 v[210:213], v[236:237], off offset:256
	s_nop 0
	s_waitcnt vmcnt(0)
	v_mov_b64_e32 v[68:69], v[182:183]
	v_mov_b64_e32 v[70:71], v[184:185]
	v_mov_b64_e32 v[64:65], v[166:167]
	v_mov_b64_e32 v[66:67], v[168:169]
	v_mov_b64_e32 v[72:73], v[170:171]
	v_mov_b64_e32 v[74:75], v[172:173]
	v_pk_add_f32 v[62:63], v[62:63], v[66:67]
	v_pk_add_f32 v[56:57], v[56:57], v[72:73]
	v_pk_add_f32 v[60:61], v[60:61], v[64:65]
	v_pk_add_f32 v[58:59], v[58:59], v[74:75]
	v_mul_f32_e32 v56, 0xbfb8aa3b, v56
	v_mul_f32_e32 v57, 0xbfb8aa3b, v57
	v_mul_f32_e32 v60, 0xbfb8aa3b, v60
	v_mul_f32_e32 v61, 0xbfb8aa3b, v61
	v_mul_f32_e32 v62, 0xbfb8aa3b, v62
	v_mul_f32_e32 v63, 0xbfb8aa3b, v63
	v_mul_f32_e32 v58, 0xbfb8aa3b, v58
	v_exp_f32_e32 v56, v56
	v_exp_f32_e32 v57, v57
	v_mul_f32_e32 v59, 0xbfb8aa3b, v59
	v_exp_f32_e32 v60, v60
	v_exp_f32_e32 v61, v61
	v_exp_f32_e32 v62, v62
	v_exp_f32_e32 v63, v63
	v_exp_f32_e32 v58, v58
	v_exp_f32_e32 v59, v59
	v_add_f32_e32 v56, 1.0, v56
	v_add_f32_e32 v57, 1.0, v57
	v_add_f32_e32 v60, 1.0, v60
	v_add_f32_e32 v61, 1.0, v61
	v_add_f32_e32 v62, 1.0, v62
	v_add_f32_e32 v63, 1.0, v63
	v_add_f32_e32 v58, 1.0, v58
	v_rcp_f32_e32 v56, v56
	v_rcp_f32_e32 v57, v57
	v_add_f32_e32 v59, 1.0, v59
	v_rcp_f32_e32 v60, v60
	v_rcp_f32_e32 v61, v61
	v_rcp_f32_e32 v62, v62
	v_rcp_f32_e32 v63, v63
	v_rcp_f32_e32 v58, v58
	v_rcp_f32_e32 v59, v59
	v_lshlrev_b32_e32 v78, 16, v70
	v_and_b32_e32 v70, 0xffff0000, v70
	v_lshlrev_b32_e32 v76, 16, v68
	v_and_b32_e32 v68, 0xffff0000, v68
	v_lshlrev_b32_e32 v77, 16, v69
	v_and_b32_e32 v69, 0xffff0000, v69
	v_lshlrev_b32_e32 v79, 16, v71
	v_mul_f32_e32 v64, v56, v78
	v_mul_f32_e32 v65, v57, v70
	v_and_b32_e32 v71, 0xffff0000, v71
	v_mul_f32_e32 v60, v60, v76
	v_mul_f32_e32 v61, v61, v68
	v_mul_f32_e32 v62, v62, v77
	v_mul_f32_e32 v63, v63, v69
	v_mul_f32_e32 v66, v58, v79
	v_cvt_pk_bf16_f32 v56, v60, v61
	v_cvt_pk_bf16_f32 v57, v62, v63
	v_cvt_pk_bf16_f32 v58, v64, v65
	v_lshl_add_u64 v[64:65], s[10:11], 0, v[86:87]
	v_mul_f32_e32 v59, v59, v71
	v_lshl_add_u64 v[68:69], v[64:65], 0, v[140:141]
	v_cvt_pk_bf16_f32 v59, v66, v59
	global_store_dwordx4 v[68:69], v[56:59], off
	v_mov_b64_e32 v[60:61], v[186:187]
	v_mov_b64_e32 v[62:63], v[188:189]
	s_nop 0
	v_mov_b64_e32 v[56:57], v[174:175]
	v_mov_b64_e32 v[58:59], v[176:177]
	v_mov_b64_e32 v[64:65], v[178:179]
	v_mov_b64_e32 v[66:67], v[180:181]
	v_add_u32_e32 v70, 0x90, v142
	v_ashrrev_i32_e32 v71, 31, v70
	v_lshlrev_b64 v[70:71], 11, v[70:71]
	v_lshl_add_u64 v[72:73], s[12:13], 0, v[70:71]
	v_lshl_add_u64 v[72:73], v[72:73], 0, v[140:141]
	v_pk_add_f32 v[54:55], v[54:55], v[58:59]
; DI float frcp(float x) { return __builtin_amdgcn_rcpf(x); }
; DI float bflo(unsigned w) { return __uint_as_float(w << 16); }
; DI float bfhi(unsigned w) { return __uint_as_float(w & 0xffff0000u); }
; DI u32x4 pack8(const f32x4 a, const f32x4 b) { u32x4 w; w.x = cvt_pk_bf16(a[0], a[1]); w.y = cvt_pk_bf16(a[2], a[3]); w.z = cvt_pk_bf16(b[0], b[1]); w.w = cvt_pk_bf16(b[2], b[3]); return w; }
;     DI void operator()(const pg8::f32x4 (&acc)[2][2][4][2], const pg8::Unit& u, int wr, int wc, int fr, int fq) const {
;     ...
;                     const int c0 = u.pn * 256 + bj * 128 + wc * 32 + 8 * fq;
;                     const u32x4 zz = *(const u32x4*)(Z + (size_t)r * SW + c0);
;                     const f32x4 b0 = *(const f32x4*)(bias + c0), b1 = *(const f32x4*)(bias + c0 + 4);
;                     const f32x4 x0 = acc[ai][bj][m][0] + b0, x1 = acc[ai][bj][m][1] + b1;
;                     f32x4 o0, o1;
;                     o0[0] = bflo(zz.x) * frcp(1.f + __expf(-x0[0])); o0[1] = bfhi(zz.x) * frcp(1.f + __expf(-x0[1]));
;                     o0[2] = bflo(zz.y) * frcp(1.f + __expf(-x0[2])); o0[3] = bfhi(zz.y) * frcp(1.f + __expf(-x0[3]));
;                     o1[0] = bflo(zz.z) * frcp(1.f + __expf(-x1[0])); o1[1] = bfhi(zz.z) * frcp(1.f + __expf(-x1[1]));
;                     o1[2] = bflo(zz.w) * frcp(1.f + __expf(-x1[2])); o1[3] = bfhi(zz.w) * frcp(1.f + __expf(-x1[3]));
;                     *(u32x4*)(S + (size_t)r * SW + c0) = pack8(o0, o1);
	v_pk_add_f32 v[50:51], v[50:51], v[66:67]
	v_pk_add_f32 v[52:53], v[52:53], v[56:57]
	v_pk_add_f32 v[48:49], v[48:49], v[64:65]
	v_mul_f32_e32 v51, 0xbfb8aa3b, v51
	v_mul_f32_e32 v52, 0xbfb8aa3b, v52
	v_mul_f32_e32 v53, 0xbfb8aa3b, v53
	v_mul_f32_e32 v54, 0xbfb8aa3b, v54
	v_mul_f32_e32 v55, 0xbfb8aa3b, v55
	v_mul_f32_e32 v48, 0xbfb8aa3b, v48
	v_mul_f32_e32 v49, 0xbfb8aa3b, v49
	v_mul_f32_e32 v50, 0xbfb8aa3b, v50
	v_exp_f32_e32 v51, v51
	v_exp_f32_e32 v52, v52
	v_exp_f32_e32 v53, v53
	v_exp_f32_e32 v54, v54
	v_exp_f32_e32 v55, v55
	v_exp_f32_e32 v48, v48
	v_exp_f32_e32 v49, v49
	v_exp_f32_e32 v50, v50
	v_add_f32_e32 v51, 1.0, v51
	v_add_f32_e32 v52, 1.0, v52
	v_add_f32_e32 v53, 1.0, v53
	v_add_f32_e32 v54, 1.0, v54
	v_add_f32_e32 v55, 1.0, v55
	v_add_f32_e32 v48, 1.0, v48
	v_add_f32_e32 v49, 1.0, v49
	v_add_f32_e32 v50, 1.0, v50
	v_rcp_f32_e32 v51, v51
	v_rcp_f32_e32 v52, v52
	v_rcp_f32_e32 v53, v53
	v_rcp_f32_e32 v54, v54
	v_rcp_f32_e32 v55, v55
	v_rcp_f32_e32 v48, v48
	v_rcp_f32_e32 v49, v49
	v_rcp_f32_e32 v50, v50
	v_lshlrev_b32_e32 v77, 16, v63
	v_and_b32_e32 v63, 0xffff0000, v63
	v_lshlrev_b32_e32 v74, 16, v60
	v_and_b32_e32 v60, 0xffff0000, v60
	v_lshlrev_b32_e32 v75, 16, v61
	v_and_b32_e32 v61, 0xffff0000, v61
	v_lshlrev_b32_e32 v76, 16, v62
	v_and_b32_e32 v62, 0xffff0000, v62
	v_mul_f32_e32 v51, v51, v63
	v_mul_f32_e32 v52, v52, v74
	v_mul_f32_e32 v53, v53, v60
	v_mul_f32_e32 v54, v54, v75
	v_mul_f32_e32 v55, v55, v61
	v_mul_f32_e32 v56, v48, v76
	v_mul_f32_e32 v57, v49, v62
	v_mul_f32_e32 v58, v50, v77
	v_cvt_pk_bf16_f32 v48, v52, v53
	v_cvt_pk_bf16_f32 v49, v54, v55
	v_cvt_pk_bf16_f32 v50, v56, v57
	v_cvt_pk_bf16_f32 v51, v58, v51
	global_store_dwordx4 v[68:69], v[48:51], off offset:256
	v_mov_b64_e32 v[52:53], v[190:191]
	v_mov_b64_e32 v[54:55], v[192:193]
	s_nop 0
	v_mov_b64_e32 v[48:49], v[166:167]
	v_mov_b64_e32 v[50:51], v[168:169]
	v_mov_b64_e32 v[56:57], v[170:171]
	v_mov_b64_e32 v[58:59], v[172:173]
	v_pk_add_f32 v[46:47], v[46:47], v[50:51]
	v_pk_add_f32 v[40:41], v[40:41], v[56:57]
	v_pk_add_f32 v[44:45], v[44:45], v[48:49]
	v_pk_add_f32 v[42:43], v[42:43], v[58:59]
	v_mul_f32_e32 v40, 0xbfb8aa3b, v40
	v_mul_f32_e32 v41, 0xbfb8aa3b, v41
	v_mul_f32_e32 v44, 0xbfb8aa3b, v44
	v_mul_f32_e32 v45, 0xbfb8aa3b, v45
	v_mul_f32_e32 v46, 0xbfb8aa3b, v46
	v_mul_f32_e32 v47, 0xbfb8aa3b, v47
	v_mul_f32_e32 v42, 0xbfb8aa3b, v42
	v_exp_f32_e32 v40, v40
	v_exp_f32_e32 v41, v41
	v_mul_f32_e32 v43, 0xbfb8aa3b, v43
	v_exp_f32_e32 v44, v44
	v_exp_f32_e32 v45, v45
	v_exp_f32_e32 v46, v46
	v_exp_f32_e32 v47, v47
	v_exp_f32_e32 v42, v42
	v_exp_f32_e32 v43, v43
	v_add_f32_e32 v40, 1.0, v40
	v_add_f32_e32 v41, 1.0, v41
	v_add_f32_e32 v44, 1.0, v44
	v_add_f32_e32 v45, 1.0, v45
	v_add_f32_e32 v46, 1.0, v46
	v_add_f32_e32 v47, 1.0, v47
	v_add_f32_e32 v42, 1.0, v42
	v_rcp_f32_e32 v40, v40
	v_rcp_f32_e32 v41, v41
	v_add_f32_e32 v43, 1.0, v43
	v_rcp_f32_e32 v44, v44
	v_rcp_f32_e32 v45, v45
	v_rcp_f32_e32 v46, v46
	v_rcp_f32_e32 v47, v47
	v_rcp_f32_e32 v42, v42
	v_rcp_f32_e32 v43, v43
	v_lshlrev_b32_e32 v62, 16, v54
	v_and_b32_e32 v54, 0xffff0000, v54
	v_lshlrev_b32_e32 v60, 16, v52
	v_and_b32_e32 v52, 0xffff0000, v52
	v_lshlrev_b32_e32 v61, 16, v53
	v_and_b32_e32 v53, 0xffff0000, v53
	v_lshlrev_b32_e32 v63, 16, v55
	v_mul_f32_e32 v48, v40, v62
	v_mul_f32_e32 v49, v41, v54
	v_and_b32_e32 v55, 0xffff0000, v55
	v_mul_f32_e32 v44, v44, v60
	v_mul_f32_e32 v45, v45, v52
	v_mul_f32_e32 v46, v46, v61
	v_mul_f32_e32 v47, v47, v53
	v_mul_f32_e32 v50, v42, v63
	v_cvt_pk_bf16_f32 v40, v44, v45
	v_cvt_pk_bf16_f32 v41, v46, v47
	v_cvt_pk_bf16_f32 v42, v48, v49
	v_lshl_add_u64 v[48:49], s[10:11], 0, v[70:71]
	v_mul_f32_e32 v43, v43, v55
	v_lshl_add_u64 v[52:53], v[48:49], 0, v[140:141]
	v_cvt_pk_bf16_f32 v43, v50, v43
	global_store_dwordx4 v[52:53], v[40:43], off
	v_mov_b64_e32 v[44:45], v[194:195]
	v_mov_b64_e32 v[46:47], v[196:197]
	s_nop 0
	v_mov_b64_e32 v[40:41], v[174:175]
	v_mov_b64_e32 v[42:43], v[176:177]
	v_mov_b64_e32 v[48:49], v[178:179]
	v_mov_b64_e32 v[50:51], v[180:181]
	v_add_u32_e32 v54, 0xa0, v142
	v_ashrrev_i32_e32 v55, 31, v54
	v_lshlrev_b64 v[54:55], 11, v[54:55]
	v_lshl_add_u64 v[56:57], s[12:13], 0, v[54:55]
	v_lshl_add_u64 v[56:57], v[56:57], 0, v[140:141]
	v_pk_add_f32 v[38:39], v[38:39], v[42:43]
	v_pk_add_f32 v[34:35], v[34:35], v[50:51]
	v_pk_add_f32 v[36:37], v[36:37], v[40:41]
	v_pk_add_f32 v[32:33], v[32:33], v[48:49]
	v_mul_f32_e32 v35, 0xbfb8aa3b, v35
	v_mul_f32_e32 v36, 0xbfb8aa3b, v36
	v_mul_f32_e32 v37, 0xbfb8aa3b, v37
	v_mul_f32_e32 v38, 0xbfb8aa3b, v38
	v_mul_f32_e32 v39, 0xbfb8aa3b, v39
	v_mul_f32_e32 v32, 0xbfb8aa3b, v32
	v_mul_f32_e32 v33, 0xbfb8aa3b, v33
	v_mul_f32_e32 v34, 0xbfb8aa3b, v34
	v_exp_f32_e32 v35, v35
	v_exp_f32_e32 v36, v36
	v_exp_f32_e32 v37, v37
	v_exp_f32_e32 v38, v38
	v_exp_f32_e32 v39, v39
	v_exp_f32_e32 v32, v32
	v_exp_f32_e32 v33, v33
	v_exp_f32_e32 v34, v34
	v_add_f32_e32 v35, 1.0, v35
	v_add_f32_e32 v36, 1.0, v36
	v_add_f32_e32 v37, 1.0, v37
	v_add_f32_e32 v38, 1.0, v38
	v_add_f32_e32 v39, 1.0, v39
	v_add_f32_e32 v32, 1.0, v32
	v_add_f32_e32 v33, 1.0, v33
	v_add_f32_e32 v34, 1.0, v34
	v_rcp_f32_e32 v35, v35
	v_rcp_f32_e32 v36, v36
	v_rcp_f32_e32 v37, v37
	v_rcp_f32_e32 v38, v38
	v_rcp_f32_e32 v39, v39
	v_rcp_f32_e32 v32, v32
	v_rcp_f32_e32 v33, v33
	v_rcp_f32_e32 v34, v34
	v_lshlrev_b32_e32 v61, 16, v47
	v_and_b32_e32 v47, 0xffff0000, v47
	v_lshlrev_b32_e32 v58, 16, v44
	v_and_b32_e32 v44, 0xffff0000, v44
	v_lshlrev_b32_e32 v59, 16, v45
	v_and_b32_e32 v45, 0xffff0000, v45
	v_lshlrev_b32_e32 v60, 16, v46
	v_and_b32_e32 v46, 0xffff0000, v46
	v_mul_f32_e32 v35, v35, v47
	v_mul_f32_e32 v36, v36, v58
; DI float frcp(float x) { return __builtin_amdgcn_rcpf(x); }
; DI float bflo(unsigned w) { return __uint_as_float(w << 16); }
; DI float bfhi(unsigned w) { return __uint_as_float(w & 0xffff0000u); }
; DI u32x4 pack8(const f32x4 a, const f32x4 b) { u32x4 w; w.x = cvt_pk_bf16(a[0], a[1]); w.y = cvt_pk_bf16(a[2], a[3]); w.z = cvt_pk_bf16(b[0], b[1]); w.w = cvt_pk_bf16(b[2], b[3]); return w; }
;     DI void operator()(const pg8::f32x4 (&acc)[2][2][4][2], const pg8::Unit& u, int wr, int wc, int fr, int fq) const {
;     ...
;                     const int c0 = u.pn * 256 + bj * 128 + wc * 32 + 8 * fq;
;                     const u32x4 zz = *(const u32x4*)(Z + (size_t)r * SW + c0);
;                     const f32x4 b0 = *(const f32x4*)(bias + c0), b1 = *(const f32x4*)(bias + c0 + 4);
;                     const f32x4 x0 = acc[ai][bj][m][0] + b0, x1 = acc[ai][bj][m][1] + b1;
;                     f32x4 o0, o1;
;                     o0[0] = bflo(zz.x) * frcp(1.f + __expf(-x0[0])); o0[1] = bfhi(zz.x) * frcp(1.f + __expf(-x0[1]));
;                     o0[2] = bflo(zz.y) * frcp(1.f + __expf(-x0[2])); o0[3] = bfhi(zz.y) * frcp(1.f + __expf(-x0[3]));
;                     o1[0] = bflo(zz.z) * frcp(1.f + __expf(-x1[0])); o1[1] = bfhi(zz.z) * frcp(1.f + __expf(-x1[1]));
;                     o1[2] = bflo(zz.w) * frcp(1.f + __expf(-x1[2])); o1[3] = bfhi(zz.w) * frcp(1.f + __expf(-x1[3]));
;                     *(u32x4*)(S + (size_t)r * SW + c0) = pack8(o0, o1);
	v_mul_f32_e32 v37, v37, v44
	v_mul_f32_e32 v38, v38, v59
	v_mul_f32_e32 v39, v39, v45
	v_mul_f32_e32 v40, v32, v60
	v_mul_f32_e32 v41, v33, v46
	v_mul_f32_e32 v42, v34, v61
	v_cvt_pk_bf16_f32 v32, v36, v37
	v_cvt_pk_bf16_f32 v33, v38, v39
	v_cvt_pk_bf16_f32 v34, v40, v41
	v_cvt_pk_bf16_f32 v35, v42, v35
	global_store_dwordx4 v[52:53], v[32:35], off offset:256
	v_mov_b64_e32 v[36:37], v[198:199]
	v_mov_b64_e32 v[38:39], v[200:201]
	s_nop 0
	v_mov_b64_e32 v[32:33], v[166:167]
	v_mov_b64_e32 v[34:35], v[168:169]
	v_mov_b64_e32 v[40:41], v[170:171]
	v_mov_b64_e32 v[42:43], v[172:173]
	v_pk_add_f32 v[30:31], v[30:31], v[34:35]
	v_pk_add_f32 v[24:25], v[24:25], v[40:41]
	v_pk_add_f32 v[28:29], v[28:29], v[32:33]
	v_pk_add_f32 v[26:27], v[26:27], v[42:43]
	v_mul_f32_e32 v24, 0xbfb8aa3b, v24
	v_mul_f32_e32 v25, 0xbfb8aa3b, v25
	v_mul_f32_e32 v28, 0xbfb8aa3b, v28
	v_mul_f32_e32 v29, 0xbfb8aa3b, v29
	v_mul_f32_e32 v30, 0xbfb8aa3b, v30
	v_mul_f32_e32 v31, 0xbfb8aa3b, v31
	v_mul_f32_e32 v26, 0xbfb8aa3b, v26
	v_exp_f32_e32 v24, v24
	v_exp_f32_e32 v25, v25
	v_mul_f32_e32 v27, 0xbfb8aa3b, v27
	v_exp_f32_e32 v28, v28
	v_exp_f32_e32 v29, v29
	v_exp_f32_e32 v30, v30
	v_exp_f32_e32 v31, v31
	v_exp_f32_e32 v26, v26
	v_exp_f32_e32 v27, v27
	v_add_f32_e32 v24, 1.0, v24
	v_add_f32_e32 v25, 1.0, v25
	v_add_f32_e32 v28, 1.0, v28
	v_add_f32_e32 v29, 1.0, v29
	v_add_f32_e32 v30, 1.0, v30
	v_add_f32_e32 v31, 1.0, v31
	v_add_f32_e32 v26, 1.0, v26
	v_rcp_f32_e32 v24, v24
	v_rcp_f32_e32 v25, v25
	v_add_f32_e32 v27, 1.0, v27
	v_rcp_f32_e32 v28, v28
	v_rcp_f32_e32 v29, v29
	v_rcp_f32_e32 v30, v30
	v_rcp_f32_e32 v31, v31
	v_rcp_f32_e32 v26, v26
	v_rcp_f32_e32 v27, v27
	v_lshlrev_b32_e32 v46, 16, v38
	v_and_b32_e32 v38, 0xffff0000, v38
	v_lshlrev_b32_e32 v44, 16, v36
	v_and_b32_e32 v36, 0xffff0000, v36
	v_lshlrev_b32_e32 v45, 16, v37
	v_and_b32_e32 v37, 0xffff0000, v37
	v_lshlrev_b32_e32 v47, 16, v39
	v_mul_f32_e32 v32, v24, v46
	v_mul_f32_e32 v33, v25, v38
	v_and_b32_e32 v39, 0xffff0000, v39
	v_mul_f32_e32 v28, v28, v44
	v_mul_f32_e32 v29, v29, v36
	v_mul_f32_e32 v30, v30, v45
	v_mul_f32_e32 v31, v31, v37
	v_mul_f32_e32 v34, v26, v47
	v_cvt_pk_bf16_f32 v24, v28, v29
	v_cvt_pk_bf16_f32 v25, v30, v31
	v_cvt_pk_bf16_f32 v26, v32, v33
	v_lshl_add_u64 v[32:33], s[10:11], 0, v[54:55]
	v_mul_f32_e32 v27, v27, v39
	v_lshl_add_u64 v[36:37], v[32:33], 0, v[140:141]
	v_cvt_pk_bf16_f32 v27, v34, v27
	global_store_dwordx4 v[36:37], v[24:27], off
	v_mov_b64_e32 v[28:29], v[202:203]
	v_mov_b64_e32 v[30:31], v[204:205]
	s_nop 0
	v_mov_b64_e32 v[24:25], v[174:175]
	v_mov_b64_e32 v[26:27], v[176:177]
	v_mov_b64_e32 v[32:33], v[178:179]
	v_mov_b64_e32 v[34:35], v[180:181]
	v_add_u32_e32 v38, 0xb0, v142
	v_ashrrev_i32_e32 v39, 31, v38
	v_lshlrev_b64 v[38:39], 11, v[38:39]
	v_lshl_add_u64 v[40:41], s[12:13], 0, v[38:39]
	v_lshl_add_u64 v[40:41], v[40:41], 0, v[140:141]
	v_pk_add_f32 v[22:23], v[22:23], v[26:27]
	v_pk_add_f32 v[18:19], v[18:19], v[34:35]
	v_pk_add_f32 v[20:21], v[20:21], v[24:25]
	v_pk_add_f32 v[16:17], v[16:17], v[32:33]
	v_mul_f32_e32 v19, 0xbfb8aa3b, v19
	v_mul_f32_e32 v20, 0xbfb8aa3b, v20
	v_mul_f32_e32 v21, 0xbfb8aa3b, v21
	v_mul_f32_e32 v22, 0xbfb8aa3b, v22
	v_mul_f32_e32 v23, 0xbfb8aa3b, v23
	v_mul_f32_e32 v16, 0xbfb8aa3b, v16
	v_mul_f32_e32 v17, 0xbfb8aa3b, v17
	v_mul_f32_e32 v18, 0xbfb8aa3b, v18
	v_exp_f32_e32 v19, v19
	v_exp_f32_e32 v20, v20
	v_exp_f32_e32 v21, v21
	v_exp_f32_e32 v22, v22
	v_exp_f32_e32 v23, v23
	v_exp_f32_e32 v16, v16
	v_exp_f32_e32 v17, v17
	v_exp_f32_e32 v18, v18
	v_add_f32_e32 v19, 1.0, v19
	v_add_f32_e32 v20, 1.0, v20
	v_add_f32_e32 v21, 1.0, v21
	v_add_f32_e32 v22, 1.0, v22
	v_add_f32_e32 v23, 1.0, v23
	v_add_f32_e32 v16, 1.0, v16
	v_add_f32_e32 v17, 1.0, v17
	v_add_f32_e32 v18, 1.0, v18
	v_rcp_f32_e32 v19, v19
	v_rcp_f32_e32 v20, v20
	v_rcp_f32_e32 v21, v21
	v_rcp_f32_e32 v22, v22
	v_rcp_f32_e32 v23, v23
	v_rcp_f32_e32 v16, v16
	v_rcp_f32_e32 v17, v17
	v_rcp_f32_e32 v18, v18
	v_lshlrev_b32_e32 v45, 16, v31
	v_and_b32_e32 v31, 0xffff0000, v31
	v_lshlrev_b32_e32 v42, 16, v28
	v_and_b32_e32 v28, 0xffff0000, v28
	v_lshlrev_b32_e32 v43, 16, v29
	v_and_b32_e32 v29, 0xffff0000, v29
	v_lshlrev_b32_e32 v44, 16, v30
	v_and_b32_e32 v30, 0xffff0000, v30
	v_mul_f32_e32 v19, v19, v31
	v_mul_f32_e32 v20, v20, v42
	v_mul_f32_e32 v21, v21, v28
	v_mul_f32_e32 v22, v22, v43
; #define PG8_BAR __builtin_amdgcn_s_barrier()
; template <class Epi, class Sched, bool ALIGN_EPI = false, bool SP2 = false>
; __device__ __forceinline__ void gemm_phase(PG8_LAS unsigned char* lds, const Gemm g, const Sched& S, const Epi& E, const int wid_in) {
;     ...
;     for (;;) {
;         const bool has_next = S.next(ui + 1, nxt);
;         const char* nA = has_next ? (const char*)g.A + (size_t)nxt.pm * tstep : cA; const char* nB = has_next ? (const char*)g.Bt + (size_t)nxt.pn * tstep : cB;
;         for (int t = 0; t < nt; t += 2) {
;             const bool last = (t == nt - 2);
;             const char* a1 = cA + (size_t)(t + 1) * kstep;
;             const char* a2 = last ? nA : cA + (size_t)(t + 2) * kstep; const char* b2 = last ? nB : cB + (size_t)(t + 2) * kstep;
;             const char* a3 = a2 + kstep; const char* b3 = b2 + kstep;
;             if (last && has_next) S.a_ready(nxt);
;             if constexpr (SP2) {
;             PG8_LDB(B0, 0, 0); PG8_LDB(B1, 0, 1); PG8_SCHED; PG8_LDA(At, 0, 0); PG8_STAGE(PG8_SA(1, 1), a1 + hstep, voffA);
;             PG8_WAIT_V(8); PG8_WAIT_L(0); PG8_BAR; PG8_MMA(0, 0, At, B0); PG8_MMA(0, 1, At, B1); PG8_BAR; PG8_SCHED;
;             PG8_LDA(At, 0, 1); PG8_STAGE(PG8_SB(0, 0), b2, voffB); PG8_STAGE(PG8_SB(0, 1), b2 + hstep, voffB); PG8_STAGE(PG8_SA(0, 0), a2, voffA);
;     DI void operator()(const pg8::f32x4 (&acc)[2][2][4][2], const pg8::Unit& u, int wr, int wc, int fr, int fq) const {
;     ...
;                     const int c0 = u.pn * 256 + bj * 128 + wc * 32 + 8 * fq;
;                     const u32x4 zz = *(const u32x4*)(Z + (size_t)r * SW + c0);
;                     const f32x4 b0 = *(const f32x4*)(bias + c0), b1 = *(const f32x4*)(bias + c0 + 4);
;                     const f32x4 x0 = acc[ai][bj][m][0] + b0, x1 = acc[ai][bj][m][1] + b1;
;                     f32x4 o0, o1;
;                     o0[0] = bflo(zz.x) * frcp(1.f + __expf(-x0[0])); o0[1] = bfhi(zz.x) * frcp(1.f + __expf(-x0[1]));
;                     o0[2] = bflo(zz.y) * frcp(1.f + __expf(-x0[2])); o0[3] = bfhi(zz.y) * frcp(1.f + __expf(-x0[3]));
;                     o1[0] = bflo(zz.z) * frcp(1.f + __expf(-x1[0])); o1[1] = bfhi(zz.z) * frcp(1.f + __expf(-x1[1]));
;                     o1[2] = bflo(zz.w) * frcp(1.f + __expf(-x1[2])); o1[3] = bfhi(zz.w) * frcp(1.f + __expf(-x1[3]));
;                     *(u32x4*)(S + (size_t)r * SW + c0) = pack8(o0, o1);
	v_mul_f32_e32 v23, v23, v29
	v_mul_f32_e32 v24, v16, v44
	v_mul_f32_e32 v25, v17, v30
	v_mul_f32_e32 v26, v18, v45
	v_cvt_pk_bf16_f32 v16, v20, v21
	v_cvt_pk_bf16_f32 v17, v22, v23
	v_cvt_pk_bf16_f32 v18, v24, v25
	v_cvt_pk_bf16_f32 v19, v26, v19
	global_store_dwordx4 v[36:37], v[16:19], off offset:256
	v_mov_b64_e32 v[20:21], v[206:207]
	v_mov_b64_e32 v[22:23], v[208:209]
	s_nop 0
	v_mov_b64_e32 v[16:17], v[166:167]
	v_mov_b64_e32 v[18:19], v[168:169]
	v_mov_b64_e32 v[24:25], v[170:171]
	v_mov_b64_e32 v[26:27], v[172:173]
	v_pk_add_f32 v[14:15], v[14:15], v[18:19]
	v_pk_add_f32 v[8:9], v[8:9], v[24:25]
	v_pk_add_f32 v[12:13], v[12:13], v[16:17]
	v_pk_add_f32 v[10:11], v[10:11], v[26:27]
	v_mul_f32_e32 v8, 0xbfb8aa3b, v8
	v_mul_f32_e32 v9, 0xbfb8aa3b, v9
	v_mul_f32_e32 v12, 0xbfb8aa3b, v12
	v_mul_f32_e32 v13, 0xbfb8aa3b, v13
	v_mul_f32_e32 v14, 0xbfb8aa3b, v14
	v_mul_f32_e32 v15, 0xbfb8aa3b, v15
	v_mul_f32_e32 v10, 0xbfb8aa3b, v10
	v_exp_f32_e32 v8, v8
	v_exp_f32_e32 v9, v9
	v_mul_f32_e32 v11, 0xbfb8aa3b, v11
	v_exp_f32_e32 v12, v12
	v_exp_f32_e32 v13, v13
	v_exp_f32_e32 v14, v14
	v_exp_f32_e32 v15, v15
	v_exp_f32_e32 v10, v10
	v_exp_f32_e32 v11, v11
	v_add_f32_e32 v8, 1.0, v8
	v_add_f32_e32 v9, 1.0, v9
	v_add_f32_e32 v12, 1.0, v12
	v_add_f32_e32 v13, 1.0, v13
	v_add_f32_e32 v14, 1.0, v14
	v_add_f32_e32 v15, 1.0, v15
	v_add_f32_e32 v10, 1.0, v10
	v_rcp_f32_e32 v8, v8
	v_rcp_f32_e32 v9, v9
	v_add_f32_e32 v11, 1.0, v11
	v_rcp_f32_e32 v12, v12
	v_rcp_f32_e32 v13, v13
	v_rcp_f32_e32 v14, v14
	v_rcp_f32_e32 v15, v15
	v_rcp_f32_e32 v10, v10
	v_rcp_f32_e32 v11, v11
	v_lshlrev_b32_e32 v30, 16, v22
	v_and_b32_e32 v22, 0xffff0000, v22
	v_lshlrev_b32_e32 v28, 16, v20
	v_and_b32_e32 v20, 0xffff0000, v20
	v_lshlrev_b32_e32 v29, 16, v21
	v_and_b32_e32 v21, 0xffff0000, v21
	v_lshlrev_b32_e32 v31, 16, v23
	v_mul_f32_e32 v16, v8, v30
	v_mul_f32_e32 v17, v9, v22
	v_and_b32_e32 v23, 0xffff0000, v23
	v_mul_f32_e32 v12, v12, v28
	v_mul_f32_e32 v13, v13, v20
	v_mul_f32_e32 v14, v14, v29
	v_mul_f32_e32 v15, v15, v21
	v_mul_f32_e32 v18, v10, v31
	v_cvt_pk_bf16_f32 v8, v12, v13
	v_cvt_pk_bf16_f32 v9, v14, v15
	v_cvt_pk_bf16_f32 v10, v16, v17
	v_lshl_add_u64 v[16:17], s[10:11], 0, v[38:39]
	v_mul_f32_e32 v11, v11, v23
	v_lshl_add_u64 v[20:21], v[16:17], 0, v[140:141]
	v_cvt_pk_bf16_f32 v11, v18, v11
	global_store_dwordx4 v[20:21], v[8:11], off
	v_mov_b64_e32 v[12:13], v[210:211]
	v_mov_b64_e32 v[14:15], v[212:213]
	s_nop 0
	v_mov_b64_e32 v[8:9], v[174:175]
	v_mov_b64_e32 v[10:11], v[176:177]
	v_mov_b64_e32 v[16:17], v[178:179]
	v_mov_b64_e32 v[18:19], v[180:181]
	v_pk_add_f32 v[6:7], v[6:7], v[10:11]
	v_pk_add_f32 v[2:3], v[2:3], v[18:19]
	v_pk_add_f32 v[4:5], v[4:5], v[8:9]
	v_pk_add_f32 v[0:1], v[0:1], v[16:17]
	v_mul_f32_e32 v3, 0xbfb8aa3b, v3
	v_mul_f32_e32 v4, 0xbfb8aa3b, v4
	v_mul_f32_e32 v5, 0xbfb8aa3b, v5
	v_mul_f32_e32 v6, 0xbfb8aa3b, v6
	v_mul_f32_e32 v7, 0xbfb8aa3b, v7
	v_mul_f32_e32 v0, 0xbfb8aa3b, v0
	v_mul_f32_e32 v1, 0xbfb8aa3b, v1
	v_mul_f32_e32 v2, 0xbfb8aa3b, v2
	v_exp_f32_e32 v3, v3
	v_exp_f32_e32 v4, v4
	v_exp_f32_e32 v5, v5
	v_exp_f32_e32 v6, v6
	v_exp_f32_e32 v7, v7
	v_exp_f32_e32 v0, v0
	v_exp_f32_e32 v1, v1
	v_exp_f32_e32 v2, v2
	v_add_f32_e32 v3, 1.0, v3
	v_add_f32_e32 v4, 1.0, v4
	v_add_f32_e32 v5, 1.0, v5
	v_add_f32_e32 v6, 1.0, v6
	v_add_f32_e32 v7, 1.0, v7
	v_add_f32_e32 v0, 1.0, v0
	v_add_f32_e32 v1, 1.0, v1
	v_add_f32_e32 v2, 1.0, v2
	v_rcp_f32_e32 v3, v3
	v_rcp_f32_e32 v4, v4
	v_rcp_f32_e32 v5, v5
	v_rcp_f32_e32 v6, v6
	v_rcp_f32_e32 v7, v7
	v_rcp_f32_e32 v0, v0
	v_rcp_f32_e32 v1, v1
	v_rcp_f32_e32 v2, v2
	v_lshlrev_b32_e32 v25, 16, v15
	v_and_b32_e32 v15, 0xffff0000, v15
	v_lshlrev_b32_e32 v22, 16, v12
	v_and_b32_e32 v12, 0xffff0000, v12
	v_lshlrev_b32_e32 v23, 16, v13
	v_and_b32_e32 v13, 0xffff0000, v13
	v_lshlrev_b32_e32 v24, 16, v14
	v_and_b32_e32 v14, 0xffff0000, v14
	v_mul_f32_e32 v3, v3, v15
	v_mul_f32_e32 v4, v4, v22
	v_mul_f32_e32 v5, v5, v12
	v_mul_f32_e32 v6, v6, v23
	v_mul_f32_e32 v7, v7, v13
	v_mul_f32_e32 v8, v0, v24
	v_mul_f32_e32 v9, v1, v14
	v_mul_f32_e32 v10, v2, v25
	v_cvt_pk_bf16_f32 v0, v4, v5
	v_cvt_pk_bf16_f32 v1, v6, v7
	v_cvt_pk_bf16_f32 v2, v8, v9
	v_cvt_pk_bf16_f32 v3, v10, v3
	global_store_dwordx4 v[20:21], v[0:3], off offset:256
	s_cbranch_vccnz .LBB0_519
	s_andn2_b64 vcc, exec, s[38:39]
	s_cbranch_vccnz .LBB0_518
	s_barrier
	s_branch .LBB0_518
